# even attention: per-XCD item queues (XCD x owns sample (b,h) pairs 4x..4x+3) with stealing; gla_seq warm-up covers all operand lines
# baseline (speedup 1.0000x reference)
.LBB0_1372:
	s_andn2_b64 vcc, exec, s[0:1]
	s_cbranch_vccnz .LBB0_1555
	s_getreg_b32 s80, hwreg(HW_REG_XCC_ID, 0, 4)
	s_and_b32 s0, s22, 16
	v_readlane_b32 s2, v252, 4
	v_readlane_b32 s3, v252, 5
	s_add_u32 s0, s0, 36
	s_lshl_b32 s0, s0, 2
	s_and_b32 s80, s80, 7
	s_mov_b32 s81, 0
	s_add_u32 s6, s2, s0
	s_addc_u32 s7, s3, 0
	v_mov_b32_e32 v0, v179
	s_waitcnt vmcnt(63) expcnt(7) lgkmcnt(15)
	s_barrier
	s_branch .LBB0_1376

.Lxq_fetch:
	s_lshl_b32 s8, s80, 2
	v_mov_b32_e32 v2, 1
	v_mov_b32_e32 v5, s8
	s_waitcnt vmcnt(0)
	global_atomic_add v2, v5, v2, s[6:7] sc0
	s_waitcnt vmcnt(0)
	v_readfirstlane_b32 s8, v2
	s_cmpk_lt_u32 s8, 0xe4
	s_cbranch_scc1 .Lxq_got
	s_add_u32 s81, s81, 1
	s_add_u32 s80, s80, 1
	s_and_b32 s80, s80, 7
	s_cmp_lt_u32 s81, 8
	s_cbranch_scc1 .Lxq_fetch
	s_mov_b32 s81, 8
	s_movk_i32 s8, 0x720
	s_branch .Lxq_put
.Lxq_got:
	s_cmp_lt_u32 s8, 4
	s_cbranch_scc0 .Lxq_m1
	s_lshl_b32 s9, s80, 2
	s_add_u32 s8, s8, s9
	s_branch .Lxq_put
.Lxq_m1:
	s_cmpk_lt_u32 s8, 0x84
	s_cbranch_scc0 .Lxq_m2
	s_lshl_b32 s9, s80, 7
	s_add_u32 s8, s8, s9
	s_add_u32 s8, s8, 28
	s_branch .Lxq_put
.Lxq_m2:
	s_cmpk_lt_u32 s8, 0xa4
	s_cbranch_scc0 .Lxq_m3
	s_lshl_b32 s9, s80, 5
	s_add_u32 s8, s8, s9
	s_addk_i32 s8, 0x39c
	s_branch .Lxq_put
.Lxq_m3:
	s_lshl_b32 s9, s80, 6
	s_add_u32 s8, s8, s9
	s_addk_i32 s8, 0x47c
.Lxq_put:
	v_mov_b32_e32 v2, s69
	v_mov_b32_e32 v0, s8
	ds_write_b32 v2, v0

.LBB0_1462:
	s_andn2_b64 vcc, exec, s[0:1]
	s_cbranch_vccnz .LBB0_1375
	s_ashr_i32 s19, s23, 3
	s_lshl_b32 s8, s19, 1
	v_readlane_b32 s2, v255, 19
	s_or_b32 s8, s8, s2
	s_waitcnt vmcnt(8)
	v_mov_b32_e32 v50, v179
	s_and_b32 s13, s23, 1
	s_ashr_i32 s9, s8, 31
	s_lshl_b64 s[8:9], s[8:9], 3
	v_ashrrev_i32_e32 v46, 6, v50
	s_lshl_b32 s20, s13, 2
	v_and_b32_e32 v52, 15, v50
	s_bfe_u32 s10, s23, 0x20001
	s_or_b32 s8, s8, s20
	s_waitcnt vmcnt(1)
	v_lshlrev_b32_e32 v2, 5, v46
	v_readlane_b32 s40, v252, 8
	s_or_b32 s8, s8, s10
	v_lshlrev_b32_e32 v0, 2, v52
	v_readlane_b32 s44, v252, 12
	v_readlane_b32 s45, v252, 13
	v_ashrrev_i32_e32 v3, 31, v2
	v_bfe_u32 v38, v50, 4, 2
	v_lshl_add_u64 v[4:5], s[44:45], 0, v[0:1]
	v_lshlrev_b64 v[34:35], 2, v[2:3]
	s_lshl_b64 s[8:9], s[8:9], 15
	v_lshl_add_u64 v[22:23], v[4:5], 0, v[34:35]
	v_lshl_or_b32 v24, v38, 11, s8
	v_mov_b32_e32 v25, s9
	v_lshl_add_u64 v[30:31], v[22:23], 0, v[24:25]
	v_add_co_u32_e32 v10, vcc, s68, v30
	s_movk_i32 s2, 0x4000
	s_nop 0
	v_addc_co_u32_e32 v11, vcc, 0, v31, vcc
	s_waitcnt vmcnt(0)
	v_or_b32_e32 v6, 0x2000, v24
	v_mov_b32_e32 v7, s9
	v_add_co_u32_e32 v18, vcc, s2, v30
	s_mov_b64 s[0:1], 0
	v_lshl_add_u64 v[14:15], v[22:23], 0, v[6:7]
	v_addc_co_u32_e32 v19, vcc, 0, v31, vcc
	global_load_dword v26, v[30:31], off
	global_load_dword v27, v[30:31], off offset:512
	global_load_dword v28, v[30:31], off offset:1024
	global_load_dword v29, v[30:31], off offset:1536
	global_load_dword v5, v[30:31], off offset:1600
	global_load_dword v4, v[30:31], off offset:1088
	global_load_dword v3, v[30:31], off offset:576
	global_load_dword v2, v[30:31], off offset:64
	global_load_dword v6, v[14:15], off
	global_load_dword v7, v[10:11], off offset:512
	global_load_dword v8, v[10:11], off offset:1024
	global_load_dword v9, v[10:11], off offset:1536
	global_load_dword v13, v[10:11], off offset:1600
	global_load_dword v12, v[10:11], off offset:1088
	s_nop 0
	global_load_dword v11, v[10:11], off offset:576
	s_nop 0
	global_load_dword v10, v[14:15], off offset:64
	v_or_b32_e32 v14, 0x4000, v24
	v_mov_b32_e32 v15, s9
	v_or_b32_e32 v24, 0x6000, v24
	v_add_co_u32_e32 v30, vcc, s29, v30
	v_lshl_add_u64 v[32:33], v[22:23], 0, v[14:15]
	v_lshl_add_u64 v[36:37], v[22:23], 0, v[24:25]
	v_addc_co_u32_e32 v31, vcc, 0, v31, vcc
	global_load_dword v14, v[32:33], off
	global_load_dword v15, v[18:19], off offset:512
	global_load_dword v16, v[18:19], off offset:1024
	global_load_dword v17, v[18:19], off offset:1536
	global_load_dword v21, v[18:19], off offset:1600
	global_load_dword v20, v[18:19], off offset:1088
	s_nop 0
	global_load_dword v19, v[18:19], off offset:576
	s_nop 0
	global_load_dword v18, v[32:33], off offset:64
	global_load_dword v22, v[36:37], off
	global_load_dword v23, v[30:31], off offset:512
	global_load_dword v24, v[30:31], off offset:1024
	global_load_dword v25, v[30:31], off offset:1536
	s_nop 0
	global_load_dword v33, v[30:31], off offset:1600
	global_load_dword v32, v[30:31], off offset:1088
	s_nop 0
	global_load_dword v31, v[30:31], off offset:576
	s_nop 0
	global_load_dword v30, v[36:37], off offset:64
	s_lshl_b32 s8, s19, 12
	s_add_i32 s28, s8, 0x2000
	s_add_u32 s20, s90, s0
	s_addc_u32 s21, s91, s1
	s_ashr_i32 s23, s28, 6
	s_mul_i32 s0, s13, 0x3000000
	v_readlane_b32 s41, v252, 9
	s_add_u32 s40, s20, s0
	s_addc_u32 s41, s21, 0
	s_cmp_eq_u32 s13, 0
	s_cselect_b64 s[34:35], -1, 0
	s_add_u32 s8, s20, 0x2993d700
	s_addc_u32 s9, s21, 0
	s_add_u32 s0, s20, 0x2b13d700
	s_addc_u32 s1, s21, 0
	s_add_u32 s44, s20, 0x2c9fd700
	v_readlane_b32 s46, v252, 14
	s_addc_u32 s45, s21, 0
	v_readlane_b32 s47, v252, 15
	s_add_u32 s46, s20, 0x2c93d700
	v_and_b32_e32 v37, 63, v50
	s_addc_u32 s47, s21, 0
	v_or_b32_e32 v60, s28, v52
	s_lshl_b32 s28, s10, 9
	s_add_u32 s40, s40, s28
	v_lshlrev_b32_e32 v47, 7, v37
	v_lshlrev_b32_e32 v53, 11, v46
	v_and_b32_e32 v0, 48, v50
	s_addc_u32 s41, s41, 0
	v_add_u32_e32 v48, v53, v47
	v_lshlrev_b32_e32 v36, 2, v38
	v_lshl_add_u64 v[42:43], s[46:47], 0, v[0:1]
	v_lshl_add_u64 v[38:39], s[0:1], 0, v[0:1]
	v_lshl_add_u64 v[40:41], s[44:45], 0, v[0:1]
	v_lshl_add_u64 v[58:59], s[40:41], 0, v[0:1]
	v_lshlrev_b32_e32 v0, 12, v46
	s_movk_i32 s2, 0xf000
	v_add_u32_e32 v46, 0xfffff800, v48
	v_add3_u32 v44, v47, v0, s2
	v_ashrrev_i32_e32 v47, 31, v46
	v_ashrrev_i32_e32 v45, 31, v44
	v_lshl_add_u64 v[46:47], s[0:1], 0, v[46:47]
	v_cmp_gt_u32_e32 vcc, 64, v50
	v_cmp_gt_u32_e64 s[0:1], 2, v37
	v_lshlrev_b32_e32 v0, 7, v50
	v_lshl_or_b32 v56, v52, 6, v53
	v_readlane_b32 s42, v252, 10
	v_readlane_b32 s43, v252, 11
	v_lshl_add_u64 v[44:45], s[44:45], 0, v[44:45]
	v_ashrrev_i32_e32 v49, 31, v48
	s_and_b64 s[44:45], vcc, s[0:1]
	v_lshl_add_u64 v[50:51], s[46:47], 0, v[0:1]
	v_ashrrev_i32_e32 v57, 31, v56
	v_lshlrev_b32_e32 v0, 7, v52
	v_lshl_add_u64 v[34:35], v[58:59], 0, v[34:35]
	s_mov_b64 s[0:1], 0x2e1fd700
	s_mov_b32 s38, 63
	s_mov_b32 s19, 2
	v_cmp_lt_u32_e64 s[40:41], 15, v37
	v_cmp_lt_u32_e64 s[42:43], 31, v37
	v_lshl_add_u64 v[48:49], s[8:9], 0, v[48:49]
	v_lshl_add_u64 v[52:53], s[8:9], 0, v[0:1]
	v_lshl_add_u64 v[54:55], v[38:39], 0, v[0:1]
	v_lshl_add_u64 v[56:57], v[56:57], 1, v[40:41]
	v_lshl_add_u64 v[58:59], v[34:35], 0, s[0:1]
	v_mov_b32_e32 v61, 0
	v_lshlrev_b32_e32 v0, 1, v36
	v_readlane_b32 s48, v252, 16
	v_readlane_b32 s49, v252, 17
	v_readlane_b32 s50, v252, 18
	v_readlane_b32 s51, v252, 19
	v_readlane_b32 s52, v252, 20
	v_readlane_b32 s53, v252, 21
	v_readlane_b32 s54, v252, 22
	v_readlane_b32 s55, v252, 23
	s_and_b64 s[0:1], s[34:35], exec
	s_cselect_b32 s1, -1, 1
	s_mul_i32 s0, s1, 0x10000
	s_mul_i32 s8, s1, 0x800
	s_ashr_i32 s1, s1, 31
	v_mov_b32_e32 v154, s0
	v_mov_b32_e32 v157, s8
	v_mov_b32_e32 v155, s1
.LBB0_1464:
	s_add_i32 s8, s38, -1
	s_add_i32 s50, s19, -1
	s_and_b64 s[0:1], s[34:35], exec
	s_cselect_b32 s28, s50, s8
	s_add_i32 s0, s28, s23
	s_lshl_b32 s0, s0, 2
	s_or_b32 s0, s0, s10
	s_lshl_b32 s1, s0, 1
	s_or_b32 s8, s1, s13
	s_and_saveexec_b64 s[46:47], s[40:41]
	s_xor_b64 s[46:47], exec, s[46:47]
	s_cbranch_execz .LBB0_1470
	s_and_saveexec_b64 s[48:49], s[42:43]
	s_xor_b64 s[48:49], exec, s[48:49]
	s_ashr_i32 s1, s0, 31
	s_lshl_b64 s[52:53], s[0:1], 14
	v_lshl_add_u64 v[36:37], v[44:45], 0, s[52:53]
	s_ashr_i32 s9, s8, 31
	s_or_saveexec_b64 s[48:49], s[48:49]
	v_mov_b64_e32 v[34:35], s[8:9]
	s_xor_b64 exec, exec, s[48:49]
	s_ashr_i32 s9, s8, 31
	s_lshl_b64 s[52:53], s[8:9], 13
	v_lshl_add_u64 v[36:37], v[46:47], 0, s[52:53]
	v_mov_b64_e32 v[34:35], s[8:9]
	s_or_b64 exec, exec, s[48:49]
.LBB0_1470:
	s_andn2_saveexec_b64 s[46:47], s[46:47]
	s_ashr_i32 s9, s8, 31
	s_lshl_b64 s[48:49], s[8:9], 13
	v_lshl_add_u64 v[36:37], v[48:49], 0, s[48:49]
	v_mov_b64_e32 v[34:35], s[8:9]
	s_or_b64 exec, exec, s[46:47]
	s_add_i32 s1, s19, -2
	s_and_b64 s[8:9], s[34:35], exec
	s_cselect_b32 s1, s1, s38
	s_add_i32 s8, s1, s23
	s_lshl_b32 s8, s8, 2
	s_or_b32 s48, s8, s10
	s_lshl_b32 s8, s48, 1
	s_or_b32 s46, s8, s13
	v_lshlrev_b64 v[38:39], 8, v[34:35]
	s_ashr_i32 s47, s46, 31
	v_lshl_add_u64 v[38:39], v[50:51], 0, v[38:39]
	s_lshl_b64 s[8:9], s[46:47], 13
	v_add_co_u32_e32 v152, vcc, v36, v154
	s_nop 1
	v_addc_co_u32_e32 v153, vcc, v37, v155, vcc
	flat_load_dword v62, v[152:153] sc0 sc1
	v_add_co_u32_e32 v152, vcc, v152, v154
	s_nop 1
	v_addc_co_u32_e32 v153, vcc, v153, v155, vcc
	flat_load_dword v156, v[152:153] sc0 sc1
	v_add_co_u32_e32 v152, vcc, v38, v157
	s_nop 1
	v_addc_co_u32_e32 v153, vcc, v39, v155, vcc
	flat_load_dword v158, v[152:153] sc0 sc1
	v_add_co_u32_e32 v152, vcc, v152, v157
	s_nop 1
	v_addc_co_u32_e32 v153, vcc, v153, v155, vcc
	flat_load_dword v159, v[152:153] sc0 sc1
	s_waitcnt vmcnt(0)
	v_lshl_add_u64 v[36:37], v[52:53], 0, s[8:9]
	v_lshl_add_u64 v[40:41], v[36:37], 0, v[0:1]
	global_load_dwordx2 v[36:37], v[40:41], off
	global_load_dwordx2 v[38:39], v[40:41], off offset:32
	global_load_dwordx2 v[64:65], v[40:41], off offset:2048
	global_load_dwordx2 v[66:67], v[40:41], off offset:2080
	v_add_co_u32_e32 v126, vcc, s14, v40
	s_ashr_i32 s49, s48, 31
	s_nop 0
	v_addc_co_u32_e32 v127, vcc, 0, v41, vcc
	global_load_dwordx2 v[68:69], v[126:127], off
	global_load_dwordx2 v[70:71], v[126:127], off offset:32
	global_load_dwordx2 v[80:81], v[40:41], off offset:64
	global_load_dwordx2 v[82:83], v[40:41], off offset:96
	global_load_dwordx2 v[88:89], v[40:41], off offset:2112
	global_load_dwordx2 v[90:91], v[40:41], off offset:2144
	global_load_dwordx2 v[96:97], v[126:127], off offset:2048
	global_load_dwordx2 v[98:99], v[126:127], off offset:2080
	s_lshl_b64 s[48:49], s[48:49], 14
	s_lshl_b64 s[46:47], s[46:47], 8
	v_lshl_add_u64 v[140:141], v[56:57], 0, s[48:49]
	v_lshl_add_u64 v[148:149], v[42:43], 0, s[46:47]
	v_lshl_add_u64 v[40:41], v[54:55], 0, s[8:9]
	global_load_dwordx4 v[100:103], v[148:149], off
	global_load_dwordx4 v[104:107], v[40:41], off
	global_load_dwordx2 v[108:109], v[126:127], off offset:64
	global_load_dwordx2 v[110:111], v[126:127], off offset:96
	global_load_dwordx4 v[116:119], v[140:141], off
	global_load_dwordx2 v[124:125], v[126:127], off offset:2112
	s_nop 0
	global_load_dwordx2 v[126:127], v[126:127], off offset:2144
	v_cvt_pk_bf16_f32 v72, v26, v27
	v_cvt_pk_bf16_f32 v73, v28, v29
	v_cvt_pk_bf16_f32 v74, v6, v7
	v_cvt_pk_bf16_f32 v75, v8, v9
	v_cvt_pk_bf16_f32 v76, v2, v3
	v_cvt_pk_bf16_f32 v77, v4, v5
	v_cvt_pk_bf16_f32 v78, v10, v11
	v_cvt_pk_bf16_f32 v79, v12, v13
	v_cvt_pk_bf16_f32 v120, v14, v15
	v_cvt_pk_bf16_f32 v121, v16, v17
	v_cvt_pk_bf16_f32 v122, v22, v23
	v_cvt_pk_bf16_f32 v123, v24, v25
	v_cvt_pk_bf16_f32 v136, v18, v19
	v_cvt_pk_bf16_f32 v137, v20, v21
	v_cvt_pk_bf16_f32 v138, v30, v31
	v_cvt_pk_bf16_f32 v139, v32, v33
	global_load_dwordx4 v[128:131], v[140:141], off offset:64
	global_load_dwordx4 v[132:135], v[40:41], off offset:64
	s_cmp_lt_u32 s50, 63
	s_mov_b64 s[8:9], -1
	s_waitcnt vmcnt(0)
	v_mfma_f32_16x16x32_bf16 v[84:87], v[72:75], v[36:39], 0
	v_mul_f32_e64 v28, v28, v102
	v_mul_f32_e64 v29, v29, v103
	v_mfma_f32_16x16x32_bf16 v[36:39], v[76:79], v[36:39], 0
	v_mul_f32_e64 v26, v26, v100
	v_mul_f32_e64 v27, v27, v101
	v_pk_mul_f32 v[4:5], v[4:5], v[102:103]
	v_pk_mul_f32 v[2:3], v[2:3], v[100:101]
	v_mfma_f32_16x16x32_bf16 v[92:95], v[72:75], v[64:67], 0
	v_mfma_f32_16x16x32_bf16 v[64:67], v[76:79], v[64:67], 0
	v_mfma_f32_16x16x32_bf16 v[112:115], v[72:75], v[68:71], 0
	v_mfma_f32_16x16x32_bf16 v[68:71], v[76:79], v[68:71], 0
	v_mfma_f32_16x16x32_bf16 v[72:75], v[72:75], v[96:99], 0
	v_mfma_f32_16x16x32_bf16 v[76:79], v[76:79], v[96:99], 0
	global_load_dwordx4 v[96:99], v[148:149], off offset:64
	s_waitcnt vmcnt(0)
	v_pk_mul_f32 v[8:9], v[8:9], v[98:99]
	v_mfma_f32_16x16x32_bf16 v[84:87], v[120:123], v[80:83], v[84:87]
	v_mul_f32_e64 v6, v6, v96
	v_mul_f32_e64 v7, v7, v97
	v_pk_mul_f32 v[12:13], v[12:13], v[98:99]
	v_pk_mul_f32 v[10:11], v[10:11], v[96:97]
	v_mfma_f32_16x16x32_bf16 v[36:39], v[136:139], v[80:83], v[36:39]
	v_mfma_f32_16x16x32_bf16 v[80:83], v[120:123], v[88:91], v[92:95]
	s_nop 2
	global_load_dwordx4 v[92:95], v[140:141], off offset:2048
	s_nop 0
	global_load_dwordx4 v[140:143], v[140:141], off offset:2112
	s_nop 0
	global_load_dwordx4 v[144:147], v[40:41], off offset:2112
	v_mfma_f32_16x16x32_bf16 v[64:67], v[136:139], v[88:91], v[64:67]
	global_load_dwordx4 v[88:91], v[40:41], off offset:2048
	v_add_co_u32_e32 v40, vcc, s14, v40
	v_mfma_f32_16x16x32_bf16 v[112:115], v[120:123], v[108:111], v[112:115]
	s_nop 0
	v_addc_co_u32_e32 v41, vcc, 0, v41, vcc
	v_mfma_f32_16x16x32_bf16 v[68:71], v[136:139], v[108:111], v[68:71]
	v_mfma_f32_16x16x32_bf16 v[72:75], v[120:123], v[124:127], v[72:75]
	global_load_dwordx4 v[108:111], v[40:41], off
	global_load_dwordx4 v[120:123], v[148:149], off offset:128
	s_waitcnt vmcnt(0)
	v_pk_mul_f32 v[16:17], v[16:17], v[122:123]
	v_mfma_f32_16x16x32_bf16 v[76:79], v[136:139], v[124:127], v[76:79]
	global_load_dwordx4 v[124:127], v[40:41], off offset:64
	global_load_dwordx4 v[136:139], v[148:149], off offset:192
	global_load_dwordx4 v[100:103], v[40:41], off offset:2112
	v_pk_mul_f32 v[14:15], v[14:15], v[120:121]
	global_load_dwordx4 v[148:151], v[40:41], off offset:2048
	v_lshl_add_u32 v40, s1, 6, v60
	v_ashrrev_i32_e32 v41, 31, v40
	v_mfma_f32_16x16x32_bf16 v[26:29], v[104:107], v[116:119], v[26:29]
	v_mul_f32_e64 v20, v20, v122
	v_mul_f32_e64 v21, v21, v123
	v_pk_mul_f32 v[18:19], v[18:19], v[120:121]
	s_waitcnt vmcnt(0)
	v_pk_mul_f32 v[24:25], v[24:25], v[138:139]
	v_mfma_f32_16x16x32_bf16 v[2:5], v[104:107], v[92:95], v[2:5]
	v_lshlrev_b64 v[104:105], 11, v[40:41]
	v_lshl_add_u64 v[104:105], v[58:59], 0, v[104:105]
	global_store_dwordx4 v[104:105], v[36:39], off offset:64
	v_pk_mul_f32 v[22:23], v[22:23], v[136:137]
	v_pk_mul_f32 v[32:33], v[32:33], v[138:139]
	v_or_b32_e32 v36, 16, v40
	v_ashrrev_i32_e32 v37, 31, v36
	v_lshlrev_b64 v[36:37], 11, v[36:37]
	v_lshl_add_u64 v[36:37], v[58:59], 0, v[36:37]
	v_pk_mul_f32 v[30:31], v[30:31], v[136:137]
	v_mfma_f32_16x16x32_bf16 v[6:9], v[88:91], v[116:119], v[6:9]
	global_store_dwordx4 v[104:105], v[84:87], off
	global_store_dwordx4 v[36:37], v[80:83], off
	global_store_dwordx4 v[36:37], v[64:67], off offset:64
	v_or_b32_e32 v36, 32, v40
	v_mfma_f32_16x16x32_bf16 v[10:13], v[88:91], v[92:95], v[10:13]
	v_ashrrev_i32_e32 v37, 31, v36
	v_lshlrev_b64 v[36:37], 11, v[36:37]
	v_lshl_add_u64 v[36:37], v[58:59], 0, v[36:37]
	v_mfma_f32_16x16x32_bf16 v[14:17], v[108:111], v[116:119], v[14:17]
	global_store_dwordx4 v[36:37], v[112:115], off
	global_store_dwordx4 v[36:37], v[68:71], off offset:64
	v_or_b32_e32 v36, 48, v40
	v_mfma_f32_16x16x32_bf16 v[18:21], v[108:111], v[92:95], v[18:21]
	v_ashrrev_i32_e32 v37, 31, v36
	v_lshlrev_b64 v[36:37], 11, v[36:37]
	v_lshl_add_u64 v[36:37], v[58:59], 0, v[36:37]
	v_mfma_f32_16x16x32_bf16 v[22:25], v[148:151], v[116:119], v[22:25]
	global_store_dwordx4 v[36:37], v[72:75], off
	global_store_dwordx4 v[36:37], v[76:79], off offset:64
	v_mfma_f32_16x16x32_bf16 v[30:33], v[148:151], v[92:95], v[30:33]
	v_mfma_f32_16x16x32_bf16 v[26:29], v[132:135], v[128:131], v[26:29]
	v_mfma_f32_16x16x32_bf16 v[2:5], v[132:135], v[140:143], v[2:5]
	v_mfma_f32_16x16x32_bf16 v[6:9], v[144:147], v[128:131], v[6:9]
	v_mfma_f32_16x16x32_bf16 v[10:13], v[144:147], v[140:143], v[10:13]
	v_mfma_f32_16x16x32_bf16 v[14:17], v[124:127], v[128:131], v[14:17]
	v_mfma_f32_16x16x32_bf16 v[18:21], v[124:127], v[140:143], v[18:21]
	v_mfma_f32_16x16x32_bf16 v[22:25], v[100:103], v[128:131], v[22:25]
	v_mfma_f32_16x16x32_bf16 v[30:33], v[100:103], v[140:143], v[30:33]
	s_cbranch_scc1 .LBB0_1474
	s_add_i32 s52, s38, -2
	s_mov_b64 s[8:9], 0
